# G1 bf16 epilogue fully rewritten (unified per-row shift-term prefetch ring, batched rstd, deferred LN-partial reductions)
# speedup vs baseline: 1.0254x; 1.0005x over previous
.LBB0_428:
	v_lshl_add_u32 v164, s34, 8, v166
	v_lshl_or_b32 v241, s30, 8, v168
	v_mov_b32_e32 v240, 0
	v_lshlrev_b32_e32 v178, 6, v164
	v_mov_b32_e32 v179, 0
	v_lshl_add_u64 v[178:179], v[150:151], 0, v[178:179]
	s_mov_b32 s25, 0x9000
	s_mov_b32 s98, 0x2000
	s_mov_b32 s99, 0
	s_and_b32 s35, s30, -4
	s_lshl_b32 s36, s30, 2
	s_and_b32 s36, s36, 12
	s_or_b32 s36, s36, s48
	s_lshl_b32 s36, s36, 3
	global_load_dwordx4 v[198:201], v[178:179], off
	global_load_dwordx4 v[202:205], v[178:179], off offset:1024
	global_load_dwordx4 v[206:209], v[178:179], off offset:2048
	global_load_dwordx4 v[210:213], v[178:179], off offset:3072
	v_lshl_add_u64 v[178:179], v[178:179], 0, s[98:99]
	global_load_dwordx4 v[224:227], v[178:179], off
	global_load_dwordx4 v[228:231], v[178:179], off offset:1024
	global_load_dwordx4 v[232:235], v[178:179], off offset:2048
	global_load_dwordx4 v[236:239], v[178:179], off offset:3072
	v_lshlrev_b32_e32 v165, 2, v241
	v_lshlrev_b32_e32 v241, 1, v241
	v_mad_u32_u24 v194, v164, s68, v241
	v_xor_b32_e32 v182, 16, v221
	v_lshlrev_b32_e32 v182, 2, v182
	v_xor_b32_e32 v183, 32, v221
	v_lshlrev_b32_e32 v183, 2, v183
	v_cmp_gt_i32_e32 vcc, s33, v164
	v_add_u32_e32 v178, s53, v164
	v_add_u32_e32 v179, s54, v164
	v_cndmask_b32_e32 v178, v178, v179, vcc
	v_cmp_gt_i32_e32 vcc, s90, v178
	v_add_u32_e32 v179, 0xffffc000, v178
	v_lshrrev_b32_e32 v179, 3, v179
	v_ashrrev_i32_e32 v180, 11, v178
	v_add_u32_e32 v179, 8, v179
	v_cndmask_b32_e32 v178, v179, v180, vcc
	v_mad_u32_u24 v240, v178, s25, v165
	global_load_dwordx4 v[56:59], v240, s[8:9]
	global_load_dwordx4 v[60:63], v240, s[8:9] offset:16
	global_load_dwordx4 v[52:55], v240, s[8:9] offset:512
	global_load_dwordx4 v[44:47], v240, s[8:9] offset:528
	s_waitcnt vmcnt(4)
	v_add_f32_e32 v156, v198, v199
	v_add_f32_e32 v170, v200, v201
	v_add_f32_e32 v157, v202, v203
	v_add_f32_e32 v171, v204, v205
	v_add_f32_e32 v158, v206, v207
	v_add_f32_e32 v172, v208, v209
	v_add_f32_e32 v159, v210, v211
	v_add_f32_e32 v173, v212, v213
	v_add_f32_e32 v160, v224, v225
	v_add_f32_e32 v174, v226, v227
	v_add_f32_e32 v161, v228, v229
	v_add_f32_e32 v175, v230, v231
	v_add_f32_e32 v162, v232, v233
	v_add_f32_e32 v176, v234, v235
	v_add_f32_e32 v163, v236, v237
	v_add_f32_e32 v177, v238, v239
	v_add_f32_e32 v156, v156, v170
	v_add_f32_e32 v157, v157, v171
	v_add_f32_e32 v158, v158, v172
	v_add_f32_e32 v159, v159, v173
	v_add_f32_e32 v160, v160, v174
	v_add_f32_e32 v161, v161, v175
	v_add_f32_e32 v162, v162, v176
	v_add_f32_e32 v163, v163, v177
	ds_bpermute_b32 v170, v182, v156
	ds_bpermute_b32 v171, v182, v157
	ds_bpermute_b32 v172, v182, v158
	ds_bpermute_b32 v173, v182, v159
	ds_bpermute_b32 v174, v182, v160
	ds_bpermute_b32 v175, v182, v161
	ds_bpermute_b32 v176, v182, v162
	ds_bpermute_b32 v177, v182, v163
	v_or_b32_e32 v181, 16, v164
	v_cmp_gt_i32_e32 vcc, s33, v181
	v_add_u32_e32 v178, s55, v164
	v_add_u32_e32 v179, s54, v181
	v_cndmask_b32_e32 v178, v178, v179, vcc
	v_cmp_gt_i32_e32 vcc, s90, v178
	v_add_u32_e32 v179, 0xffffc000, v178
	v_lshrrev_b32_e32 v179, 3, v179
	v_ashrrev_i32_e32 v180, 11, v178
	v_add_u32_e32 v179, 8, v179
	v_cndmask_b32_e32 v178, v179, v180, vcc
	v_mad_u32_u24 v240, v178, s25, v165
	global_load_dwordx4 v[198:201], v240, s[8:9]
	global_load_dwordx4 v[202:205], v240, s[8:9] offset:16
	global_load_dwordx4 v[206:209], v240, s[8:9] offset:512
	global_load_dwordx4 v[210:213], v240, s[8:9] offset:528
	s_waitcnt lgkmcnt(0)
	v_add_f32_e32 v156, v156, v170
	v_add_f32_e32 v157, v157, v171
	v_add_f32_e32 v158, v158, v172
	v_add_f32_e32 v159, v159, v173
	v_add_f32_e32 v160, v160, v174
	v_add_f32_e32 v161, v161, v175
	v_add_f32_e32 v162, v162, v176
	v_add_f32_e32 v163, v163, v177
	ds_bpermute_b32 v170, v183, v156
	ds_bpermute_b32 v171, v183, v157
	ds_bpermute_b32 v172, v183, v158
	ds_bpermute_b32 v173, v183, v159
	ds_bpermute_b32 v174, v183, v160
	ds_bpermute_b32 v175, v183, v161
	ds_bpermute_b32 v176, v183, v162
	ds_bpermute_b32 v177, v183, v163
	v_or_b32_e32 v181, 32, v164
	v_cmp_gt_i32_e32 vcc, s33, v181
	v_add_u32_e32 v178, s56, v164
	v_add_u32_e32 v179, s54, v181
	v_cndmask_b32_e32 v178, v178, v179, vcc
	v_cmp_gt_i32_e32 vcc, s90, v178
	v_add_u32_e32 v179, 0xffffc000, v178
	v_lshrrev_b32_e32 v179, 3, v179
	v_ashrrev_i32_e32 v180, 11, v178
	v_add_u32_e32 v179, 8, v179
	v_cndmask_b32_e32 v178, v179, v180, vcc
	v_mad_u32_u24 v240, v178, s25, v165
	global_load_dwordx4 v[224:227], v240, s[8:9]
	global_load_dwordx4 v[228:231], v240, s[8:9] offset:16
	global_load_dwordx4 v[232:235], v240, s[8:9] offset:512
	global_load_dwordx4 v[236:239], v240, s[8:9] offset:528
	s_waitcnt lgkmcnt(0)
	v_add_f32_e32 v156, v156, v170
	v_add_f32_e32 v157, v157, v171
	v_add_f32_e32 v158, v158, v172
	v_add_f32_e32 v159, v159, v173
	v_add_f32_e32 v160, v160, v174
	v_add_f32_e32 v161, v161, v175
	v_add_f32_e32 v162, v162, v176
	v_add_f32_e32 v163, v163, v177
	v_fmamk_f32 v156, v156, 0x3a800000, v216
	v_fmamk_f32 v157, v157, 0x3a800000, v216
	v_fmamk_f32 v158, v158, 0x3a800000, v216
	v_fmamk_f32 v159, v159, 0x3a800000, v216
	v_fmamk_f32 v160, v160, 0x3a800000, v216
	v_fmamk_f32 v161, v161, 0x3a800000, v216
	v_fmamk_f32 v162, v162, 0x3a800000, v216
	v_fmamk_f32 v163, v163, 0x3a800000, v216
	v_rsq_f32_e32 v156, v156
	v_rsq_f32_e32 v157, v157
	v_rsq_f32_e32 v158, v158
	v_rsq_f32_e32 v159, v159
	v_rsq_f32_e32 v160, v160
	v_rsq_f32_e32 v161, v161
	v_rsq_f32_e32 v162, v162
	v_rsq_f32_e32 v163, v163
	s_nop 0
	s_waitcnt vmcnt(8)
	v_pk_fma_f32 v[142:143], v[142:143], v[156:157], v[58:59] op_sel_hi:[1,0,1]
	v_pk_fma_f32 v[140:141], v[140:141], v[156:157], v[56:57] op_sel_hi:[1,0,1]
	v_pk_fma_f32 v[138:139], v[138:139], v[156:157], v[62:63] op_sel_hi:[1,0,1]
	v_pk_fma_f32 v[136:137], v[136:137], v[156:157], v[60:61] op_sel_hi:[1,0,1]
	v_pk_fma_f32 v[134:135], v[134:135], v[156:157], v[54:55] op_sel_hi:[1,0,1]
	v_pk_fma_f32 v[132:133], v[132:133], v[156:157], v[52:53] op_sel_hi:[1,0,1]
	v_pk_fma_f32 v[130:131], v[130:131], v[156:157], v[46:47] op_sel_hi:[1,0,1]
	v_pk_fma_f32 v[128:129], v[128:129], v[156:157], v[44:45] op_sel_hi:[1,0,1]
	s_cmp_lg_u32 s35, 8
	s_cbranch_scc1 .Lg1e_nv0
	v_add_f32_e32 v180, v140, v136
	v_mul_f32_e32 v181, v140, v140
	v_fmac_f32_e32 v181, v136, v136
	v_add_f32_e32 v178, 0, v180
	v_add_f32_e32 v179, 0, v181
	v_add_f32_e32 v180, v141, v137
	v_mul_f32_e32 v181, v141, v141
	v_fmac_f32_e32 v181, v137, v137
	v_add_f32_e32 v178, v178, v180
	v_add_f32_e32 v179, v179, v181
	v_add_f32_e32 v180, v142, v138
	v_mul_f32_e32 v181, v142, v142
	v_fmac_f32_e32 v181, v138, v138
	v_add_f32_e32 v178, v178, v180
	v_add_f32_e32 v179, v179, v181
	v_add_f32_e32 v180, v143, v139
	v_mul_f32_e32 v181, v143, v143
	v_fmac_f32_e32 v181, v139, v139
	v_add_f32_e32 v178, v178, v180
	v_add_f32_e32 v179, v179, v181
	v_add_f32_e32 v180, v132, v128
	v_mul_f32_e32 v181, v132, v132
	v_fmac_f32_e32 v181, v128, v128
	v_add_f32_e32 v178, v178, v180
	v_add_f32_e32 v179, v179, v181
	v_add_f32_e32 v180, v133, v129
	v_mul_f32_e32 v181, v133, v133
	v_fmac_f32_e32 v181, v129, v129
	v_add_f32_e32 v178, v178, v180
	v_add_f32_e32 v179, v179, v181
	v_add_f32_e32 v180, v134, v130
	v_mul_f32_e32 v181, v134, v134
	v_fmac_f32_e32 v181, v130, v130
	v_add_f32_e32 v178, v178, v180
	v_add_f32_e32 v179, v179, v181
	v_add_f32_e32 v180, v135, v131
	v_mul_f32_e32 v181, v135, v135
	v_fmac_f32_e32 v181, v131, v131
	v_add_f32_e32 v178, v178, v180
	v_add_f32_e32 v179, v179, v181
.Lg1e_nv0:
	v_cvt_pk_bf16_f32 v140, v140, v141
	v_cvt_pk_bf16_f32 v141, v142, v143
	v_cvt_pk_bf16_f32 v142, v136, v137
	v_cvt_pk_bf16_f32 v143, v138, v139
	global_store_dwordx4 v194, v[140:143], s[6:7]
	v_cvt_pk_bf16_f32 v132, v132, v133
	v_cvt_pk_bf16_f32 v133, v134, v135
	v_cvt_pk_bf16_f32 v134, v128, v129
	v_cvt_pk_bf16_f32 v135, v130, v131
	global_store_dwordx4 v194, v[132:135], s[6:7] offset:256
	v_mov_b32_e32 v136, v178
	v_mov_b32_e32 v137, v179
	v_add_u32_e32 v197, 0x48000, v194
	v_or_b32_e32 v181, 48, v164
	v_cmp_gt_i32_e32 vcc, s33, v181
	v_add_u32_e32 v178, s57, v164
	v_add_u32_e32 v179, s54, v181
	v_cndmask_b32_e32 v178, v178, v179, vcc
	v_cmp_gt_i32_e32 vcc, s90, v178
	v_add_u32_e32 v179, 0xffffc000, v178
	v_lshrrev_b32_e32 v179, 3, v179
	v_ashrrev_i32_e32 v180, 11, v178
	v_add_u32_e32 v179, 8, v179
	v_cndmask_b32_e32 v178, v179, v180, vcc
	v_mad_u32_u24 v240, v178, s25, v165
	global_load_dwordx4 v[56:59], v240, s[8:9]
	global_load_dwordx4 v[60:63], v240, s[8:9] offset:16
	global_load_dwordx4 v[52:55], v240, s[8:9] offset:512
	global_load_dwordx4 v[44:47], v240, s[8:9] offset:528
	s_waitcnt vmcnt(10)
	v_pk_fma_f32 v[126:127], v[126:127], v[156:157], v[200:201] op_sel:[0,1,0] op_sel_hi:[1,1,1]
	v_pk_fma_f32 v[124:125], v[124:125], v[156:157], v[198:199] op_sel:[0,1,0] op_sel_hi:[1,1,1]
	v_pk_fma_f32 v[122:123], v[122:123], v[156:157], v[204:205] op_sel:[0,1,0] op_sel_hi:[1,1,1]
	v_pk_fma_f32 v[120:121], v[120:121], v[156:157], v[202:203] op_sel:[0,1,0] op_sel_hi:[1,1,1]
	v_pk_fma_f32 v[118:119], v[118:119], v[156:157], v[208:209] op_sel:[0,1,0] op_sel_hi:[1,1,1]
	v_pk_fma_f32 v[116:117], v[116:117], v[156:157], v[206:207] op_sel:[0,1,0] op_sel_hi:[1,1,1]
	v_pk_fma_f32 v[114:115], v[114:115], v[156:157], v[212:213] op_sel:[0,1,0] op_sel_hi:[1,1,1]
	v_pk_fma_f32 v[112:113], v[112:113], v[156:157], v[210:211] op_sel:[0,1,0] op_sel_hi:[1,1,1]
	s_cmp_lg_u32 s35, 8
	s_cbranch_scc1 .Lg1e_nv1
	v_add_f32_e32 v180, v124, v120
	v_mul_f32_e32 v181, v124, v124
	v_fmac_f32_e32 v181, v120, v120
	v_add_f32_e32 v178, 0, v180
	v_add_f32_e32 v179, 0, v181
	v_add_f32_e32 v180, v125, v121
	v_mul_f32_e32 v181, v125, v125
	v_fmac_f32_e32 v181, v121, v121
	v_add_f32_e32 v178, v178, v180
	v_add_f32_e32 v179, v179, v181
	v_add_f32_e32 v180, v126, v122
	v_mul_f32_e32 v181, v126, v126
	v_fmac_f32_e32 v181, v122, v122
	v_add_f32_e32 v178, v178, v180
	v_add_f32_e32 v179, v179, v181
	v_add_f32_e32 v180, v127, v123
	v_mul_f32_e32 v181, v127, v127
	v_fmac_f32_e32 v181, v123, v123
	v_add_f32_e32 v178, v178, v180
	v_add_f32_e32 v179, v179, v181
	v_add_f32_e32 v180, v116, v112
	v_mul_f32_e32 v181, v116, v116
	v_fmac_f32_e32 v181, v112, v112
	v_add_f32_e32 v178, v178, v180
	v_add_f32_e32 v179, v179, v181
	v_add_f32_e32 v180, v117, v113
	v_mul_f32_e32 v181, v117, v117
	v_fmac_f32_e32 v181, v113, v113
	v_add_f32_e32 v178, v178, v180
	v_add_f32_e32 v179, v179, v181
	v_add_f32_e32 v180, v118, v114
	v_mul_f32_e32 v181, v118, v118
	v_fmac_f32_e32 v181, v114, v114
	v_add_f32_e32 v178, v178, v180
	v_add_f32_e32 v179, v179, v181
	v_add_f32_e32 v180, v119, v115
	v_mul_f32_e32 v181, v119, v119
	v_fmac_f32_e32 v181, v115, v115
	v_add_f32_e32 v178, v178, v180
	v_add_f32_e32 v179, v179, v181
.Lg1e_nv1:
	v_cvt_pk_bf16_f32 v124, v124, v125
	v_cvt_pk_bf16_f32 v125, v126, v127
	v_cvt_pk_bf16_f32 v126, v120, v121
	v_cvt_pk_bf16_f32 v127, v122, v123
	global_store_dwordx4 v197, v[124:127], s[6:7]
	v_cvt_pk_bf16_f32 v116, v116, v117
	v_cvt_pk_bf16_f32 v117, v118, v119
	v_cvt_pk_bf16_f32 v118, v112, v113
	v_cvt_pk_bf16_f32 v119, v114, v115
	global_store_dwordx4 v197, v[116:119], s[6:7] offset:256
	v_mov_b32_e32 v120, v178
	v_mov_b32_e32 v121, v179
	v_add_u32_e32 v194, 0x48000, v197
	v_add_u32_e32 v181, 0x80, v164
	v_cmp_gt_i32_e32 vcc, s33, v181
	v_add_u32_e32 v178, s58, v164
	v_add_u32_e32 v179, s54, v181
	v_cndmask_b32_e32 v178, v178, v179, vcc
	v_cmp_gt_i32_e32 vcc, s90, v178
	v_add_u32_e32 v179, 0xffffc000, v178
	v_lshrrev_b32_e32 v179, 3, v179
	v_ashrrev_i32_e32 v180, 11, v178
	v_add_u32_e32 v179, 8, v179
	v_cndmask_b32_e32 v178, v179, v180, vcc
	v_mad_u32_u24 v240, v178, s25, v165
	global_load_dwordx4 v[198:201], v240, s[8:9]
	global_load_dwordx4 v[202:205], v240, s[8:9] offset:16
	global_load_dwordx4 v[206:209], v240, s[8:9] offset:512
	global_load_dwordx4 v[210:213], v240, s[8:9] offset:528
	s_waitcnt vmcnt(12)
	v_pk_fma_f32 v[110:111], v[110:111], v[158:159], v[226:227] op_sel_hi:[1,0,1]
	v_pk_fma_f32 v[108:109], v[108:109], v[158:159], v[224:225] op_sel_hi:[1,0,1]
	v_pk_fma_f32 v[106:107], v[106:107], v[158:159], v[230:231] op_sel_hi:[1,0,1]
	v_pk_fma_f32 v[104:105], v[104:105], v[158:159], v[228:229] op_sel_hi:[1,0,1]
	v_pk_fma_f32 v[102:103], v[102:103], v[158:159], v[234:235] op_sel_hi:[1,0,1]
	v_pk_fma_f32 v[100:101], v[100:101], v[158:159], v[232:233] op_sel_hi:[1,0,1]
	v_pk_fma_f32 v[98:99], v[98:99], v[158:159], v[238:239] op_sel_hi:[1,0,1]
	v_pk_fma_f32 v[96:97], v[96:97], v[158:159], v[236:237] op_sel_hi:[1,0,1]
	s_cmp_lg_u32 s35, 8
	s_cbranch_scc1 .Lg1e_nv2
	v_add_f32_e32 v180, v108, v104
	v_mul_f32_e32 v181, v108, v108
	v_fmac_f32_e32 v181, v104, v104
	v_add_f32_e32 v178, 0, v180
	v_add_f32_e32 v179, 0, v181
	v_add_f32_e32 v180, v109, v105
	v_mul_f32_e32 v181, v109, v109
	v_fmac_f32_e32 v181, v105, v105
	v_add_f32_e32 v178, v178, v180
	v_add_f32_e32 v179, v179, v181
	v_add_f32_e32 v180, v110, v106
	v_mul_f32_e32 v181, v110, v110
	v_fmac_f32_e32 v181, v106, v106
	v_add_f32_e32 v178, v178, v180
	v_add_f32_e32 v179, v179, v181
	v_add_f32_e32 v180, v111, v107
	v_mul_f32_e32 v181, v111, v111
	v_fmac_f32_e32 v181, v107, v107
	v_add_f32_e32 v178, v178, v180
	v_add_f32_e32 v179, v179, v181
	v_add_f32_e32 v180, v100, v96
	v_mul_f32_e32 v181, v100, v100
	v_fmac_f32_e32 v181, v96, v96
	v_add_f32_e32 v178, v178, v180
	v_add_f32_e32 v179, v179, v181
	v_add_f32_e32 v180, v101, v97
	v_mul_f32_e32 v181, v101, v101
	v_fmac_f32_e32 v181, v97, v97
	v_add_f32_e32 v178, v178, v180
	v_add_f32_e32 v179, v179, v181
	v_add_f32_e32 v180, v102, v98
	v_mul_f32_e32 v181, v102, v102
	v_fmac_f32_e32 v181, v98, v98
	v_add_f32_e32 v178, v178, v180
	v_add_f32_e32 v179, v179, v181
	v_add_f32_e32 v180, v103, v99
	v_mul_f32_e32 v181, v103, v103
	v_fmac_f32_e32 v181, v99, v99
	v_add_f32_e32 v178, v178, v180
	v_add_f32_e32 v179, v179, v181
.Lg1e_nv2:
	v_cvt_pk_bf16_f32 v108, v108, v109
	v_cvt_pk_bf16_f32 v109, v110, v111
	v_cvt_pk_bf16_f32 v110, v104, v105
	v_cvt_pk_bf16_f32 v111, v106, v107
	global_store_dwordx4 v194, v[108:111], s[6:7]
	v_cvt_pk_bf16_f32 v100, v100, v101
	v_cvt_pk_bf16_f32 v101, v102, v103
	v_cvt_pk_bf16_f32 v102, v96, v97
	v_cvt_pk_bf16_f32 v103, v98, v99
	global_store_dwordx4 v194, v[100:103], s[6:7] offset:256
	v_mov_b32_e32 v104, v178
	v_mov_b32_e32 v105, v179
	v_add_u32_e32 v197, 0x48000, v194
	v_add_u32_e32 v181, 0x90, v164
	v_cmp_gt_i32_e32 vcc, s33, v181
	v_add_u32_e32 v178, s59, v164
	v_add_u32_e32 v179, s54, v181
	v_cndmask_b32_e32 v178, v178, v179, vcc
	v_cmp_gt_i32_e32 vcc, s90, v178
	v_add_u32_e32 v179, 0xffffc000, v178
	v_lshrrev_b32_e32 v179, 3, v179
	v_ashrrev_i32_e32 v180, 11, v178
	v_add_u32_e32 v179, 8, v179
	v_cndmask_b32_e32 v178, v179, v180, vcc
	v_mad_u32_u24 v240, v178, s25, v165
	global_load_dwordx4 v[224:227], v240, s[8:9]
	global_load_dwordx4 v[228:231], v240, s[8:9] offset:16
	global_load_dwordx4 v[232:235], v240, s[8:9] offset:512
	global_load_dwordx4 v[236:239], v240, s[8:9] offset:528
	s_waitcnt vmcnt(12)
	v_pk_fma_f32 v[94:95], v[94:95], v[158:159], v[58:59] op_sel:[0,1,0] op_sel_hi:[1,1,1]
	v_pk_fma_f32 v[92:93], v[92:93], v[158:159], v[56:57] op_sel:[0,1,0] op_sel_hi:[1,1,1]
	v_pk_fma_f32 v[90:91], v[90:91], v[158:159], v[62:63] op_sel:[0,1,0] op_sel_hi:[1,1,1]
	v_pk_fma_f32 v[88:89], v[88:89], v[158:159], v[60:61] op_sel:[0,1,0] op_sel_hi:[1,1,1]
	v_pk_fma_f32 v[86:87], v[86:87], v[158:159], v[54:55] op_sel:[0,1,0] op_sel_hi:[1,1,1]
	v_pk_fma_f32 v[84:85], v[84:85], v[158:159], v[52:53] op_sel:[0,1,0] op_sel_hi:[1,1,1]
	v_pk_fma_f32 v[82:83], v[82:83], v[158:159], v[46:47] op_sel:[0,1,0] op_sel_hi:[1,1,1]
	v_pk_fma_f32 v[80:81], v[80:81], v[158:159], v[44:45] op_sel:[0,1,0] op_sel_hi:[1,1,1]
	s_cmp_lg_u32 s35, 8
	s_cbranch_scc1 .Lg1e_nv3
	v_add_f32_e32 v180, v92, v88
	v_mul_f32_e32 v181, v92, v92
	v_fmac_f32_e32 v181, v88, v88
	v_add_f32_e32 v178, 0, v180
	v_add_f32_e32 v179, 0, v181
	v_add_f32_e32 v180, v93, v89
	v_mul_f32_e32 v181, v93, v93
	v_fmac_f32_e32 v181, v89, v89
	v_add_f32_e32 v178, v178, v180
	v_add_f32_e32 v179, v179, v181
	v_add_f32_e32 v180, v94, v90
	v_mul_f32_e32 v181, v94, v94
	v_fmac_f32_e32 v181, v90, v90
	v_add_f32_e32 v178, v178, v180
	v_add_f32_e32 v179, v179, v181
	v_add_f32_e32 v180, v95, v91
	v_mul_f32_e32 v181, v95, v95
	v_fmac_f32_e32 v181, v91, v91
	v_add_f32_e32 v178, v178, v180
	v_add_f32_e32 v179, v179, v181
	v_add_f32_e32 v180, v84, v80
	v_mul_f32_e32 v181, v84, v84
	v_fmac_f32_e32 v181, v80, v80
	v_add_f32_e32 v178, v178, v180
	v_add_f32_e32 v179, v179, v181
	v_add_f32_e32 v180, v85, v81
	v_mul_f32_e32 v181, v85, v85
	v_fmac_f32_e32 v181, v81, v81
	v_add_f32_e32 v178, v178, v180
	v_add_f32_e32 v179, v179, v181
	v_add_f32_e32 v180, v86, v82
	v_mul_f32_e32 v181, v86, v86
	v_fmac_f32_e32 v181, v82, v82
	v_add_f32_e32 v178, v178, v180
	v_add_f32_e32 v179, v179, v181
	v_add_f32_e32 v180, v87, v83
	v_mul_f32_e32 v181, v87, v87
	v_fmac_f32_e32 v181, v83, v83
	v_add_f32_e32 v178, v178, v180
	v_add_f32_e32 v179, v179, v181
.Lg1e_nv3:
	v_cvt_pk_bf16_f32 v92, v92, v93
	v_cvt_pk_bf16_f32 v93, v94, v95
	v_cvt_pk_bf16_f32 v94, v88, v89
	v_cvt_pk_bf16_f32 v95, v90, v91
	global_store_dwordx4 v197, v[92:95], s[6:7]
	v_cvt_pk_bf16_f32 v84, v84, v85
	v_cvt_pk_bf16_f32 v85, v86, v87
	v_cvt_pk_bf16_f32 v86, v80, v81
	v_cvt_pk_bf16_f32 v87, v82, v83
	global_store_dwordx4 v197, v[84:87], s[6:7] offset:256
	v_mov_b32_e32 v88, v178
	v_mov_b32_e32 v89, v179
	v_add_u32_e32 v194, 0x168000, v197
	v_add_u32_e32 v181, 0xa0, v164
	v_cmp_gt_i32_e32 vcc, s33, v181
	v_add_u32_e32 v178, s60, v164
	v_add_u32_e32 v179, s54, v181
	v_cndmask_b32_e32 v178, v178, v179, vcc
	v_cmp_gt_i32_e32 vcc, s90, v178
	v_add_u32_e32 v179, 0xffffc000, v178
	v_lshrrev_b32_e32 v179, 3, v179
	v_ashrrev_i32_e32 v180, 11, v178
	v_add_u32_e32 v179, 8, v179
	v_cndmask_b32_e32 v178, v179, v180, vcc
	v_mad_u32_u24 v240, v178, s25, v165
	global_load_dwordx4 v[56:59], v240, s[8:9]
	global_load_dwordx4 v[60:63], v240, s[8:9] offset:16
	global_load_dwordx4 v[52:55], v240, s[8:9] offset:512
	global_load_dwordx4 v[44:47], v240, s[8:9] offset:528
	s_waitcnt vmcnt(12)
	v_pk_fma_f32 v[78:79], v[78:79], v[160:161], v[200:201] op_sel_hi:[1,0,1]
	v_pk_fma_f32 v[76:77], v[76:77], v[160:161], v[198:199] op_sel_hi:[1,0,1]
	v_pk_fma_f32 v[74:75], v[74:75], v[160:161], v[204:205] op_sel_hi:[1,0,1]
	v_pk_fma_f32 v[72:73], v[72:73], v[160:161], v[202:203] op_sel_hi:[1,0,1]
	v_pk_fma_f32 v[70:71], v[70:71], v[160:161], v[208:209] op_sel_hi:[1,0,1]
	v_pk_fma_f32 v[68:69], v[68:69], v[160:161], v[206:207] op_sel_hi:[1,0,1]
	v_pk_fma_f32 v[66:67], v[66:67], v[160:161], v[212:213] op_sel_hi:[1,0,1]
	v_pk_fma_f32 v[64:65], v[64:65], v[160:161], v[210:211] op_sel_hi:[1,0,1]
	s_cmp_lg_u32 s35, 8
	s_cbranch_scc1 .Lg1e_nv4
	v_add_f32_e32 v180, v76, v72
	v_mul_f32_e32 v181, v76, v76
	v_fmac_f32_e32 v181, v72, v72
	v_add_f32_e32 v178, 0, v180
	v_add_f32_e32 v179, 0, v181
	v_add_f32_e32 v180, v77, v73
	v_mul_f32_e32 v181, v77, v77
	v_fmac_f32_e32 v181, v73, v73
	v_add_f32_e32 v178, v178, v180
	v_add_f32_e32 v179, v179, v181
	v_add_f32_e32 v180, v78, v74
	v_mul_f32_e32 v181, v78, v78
	v_fmac_f32_e32 v181, v74, v74
	v_add_f32_e32 v178, v178, v180
	v_add_f32_e32 v179, v179, v181
	v_add_f32_e32 v180, v79, v75
	v_mul_f32_e32 v181, v79, v79
	v_fmac_f32_e32 v181, v75, v75
	v_add_f32_e32 v178, v178, v180
	v_add_f32_e32 v179, v179, v181
	v_add_f32_e32 v180, v68, v64
	v_mul_f32_e32 v181, v68, v68
	v_fmac_f32_e32 v181, v64, v64
	v_add_f32_e32 v178, v178, v180
	v_add_f32_e32 v179, v179, v181
	v_add_f32_e32 v180, v69, v65
	v_mul_f32_e32 v181, v69, v69
	v_fmac_f32_e32 v181, v65, v65
	v_add_f32_e32 v178, v178, v180
	v_add_f32_e32 v179, v179, v181
	v_add_f32_e32 v180, v70, v66
	v_mul_f32_e32 v181, v70, v70
	v_fmac_f32_e32 v181, v66, v66
	v_add_f32_e32 v178, v178, v180
	v_add_f32_e32 v179, v179, v181
	v_add_f32_e32 v180, v71, v67
	v_mul_f32_e32 v181, v71, v71
	v_fmac_f32_e32 v181, v67, v67
	v_add_f32_e32 v178, v178, v180
	v_add_f32_e32 v179, v179, v181
.Lg1e_nv4:
	v_cvt_pk_bf16_f32 v76, v76, v77
	v_cvt_pk_bf16_f32 v77, v78, v79
	v_cvt_pk_bf16_f32 v78, v72, v73
	v_cvt_pk_bf16_f32 v79, v74, v75
	global_store_dwordx4 v194, v[76:79], s[6:7]
	v_cvt_pk_bf16_f32 v68, v68, v69
	v_cvt_pk_bf16_f32 v69, v70, v71
	v_cvt_pk_bf16_f32 v70, v64, v65
	v_cvt_pk_bf16_f32 v71, v66, v67
	global_store_dwordx4 v194, v[68:71], s[6:7] offset:256
	v_mov_b32_e32 v72, v178
	v_mov_b32_e32 v73, v179
	v_add_u32_e32 v197, 0x48000, v194
	v_add_u32_e32 v181, 0xb0, v164
	v_cmp_gt_i32_e32 vcc, s33, v181
	v_add_u32_e32 v178, s61, v164
	v_add_u32_e32 v179, s54, v181
	v_cndmask_b32_e32 v178, v178, v179, vcc
	v_cmp_gt_i32_e32 vcc, s90, v178
	v_add_u32_e32 v179, 0xffffc000, v178
	v_lshrrev_b32_e32 v179, 3, v179
	v_ashrrev_i32_e32 v180, 11, v178
	v_add_u32_e32 v179, 8, v179
	v_cndmask_b32_e32 v178, v179, v180, vcc
	v_mad_u32_u24 v240, v178, s25, v165
	global_load_dwordx4 v[198:201], v240, s[8:9]
	global_load_dwordx4 v[202:205], v240, s[8:9] offset:16
	global_load_dwordx4 v[206:209], v240, s[8:9] offset:512
	global_load_dwordx4 v[210:213], v240, s[8:9] offset:528
	s_waitcnt vmcnt(12)
	v_pk_fma_f32 v[50:51], v[50:51], v[160:161], v[226:227] op_sel:[0,1,0] op_sel_hi:[1,1,1]
	v_pk_fma_f32 v[48:49], v[48:49], v[160:161], v[224:225] op_sel:[0,1,0] op_sel_hi:[1,1,1]
	v_pk_fma_f32 v[42:43], v[42:43], v[160:161], v[230:231] op_sel:[0,1,0] op_sel_hi:[1,1,1]
	v_pk_fma_f32 v[40:41], v[40:41], v[160:161], v[228:229] op_sel:[0,1,0] op_sel_hi:[1,1,1]
	v_pk_fma_f32 v[38:39], v[38:39], v[160:161], v[234:235] op_sel:[0,1,0] op_sel_hi:[1,1,1]
	v_pk_fma_f32 v[36:37], v[36:37], v[160:161], v[232:233] op_sel:[0,1,0] op_sel_hi:[1,1,1]
	v_pk_fma_f32 v[34:35], v[34:35], v[160:161], v[238:239] op_sel:[0,1,0] op_sel_hi:[1,1,1]
	v_pk_fma_f32 v[32:33], v[32:33], v[160:161], v[236:237] op_sel:[0,1,0] op_sel_hi:[1,1,1]
	s_cmp_lg_u32 s35, 8
	s_cbranch_scc1 .Lg1e_nv5
	v_add_f32_e32 v180, v48, v40
	v_mul_f32_e32 v181, v48, v48
	v_fmac_f32_e32 v181, v40, v40
	v_add_f32_e32 v178, 0, v180
	v_add_f32_e32 v179, 0, v181
	v_add_f32_e32 v180, v49, v41
	v_mul_f32_e32 v181, v49, v49
	v_fmac_f32_e32 v181, v41, v41
	v_add_f32_e32 v178, v178, v180
	v_add_f32_e32 v179, v179, v181
	v_add_f32_e32 v180, v50, v42
	v_mul_f32_e32 v181, v50, v50
	v_fmac_f32_e32 v181, v42, v42
	v_add_f32_e32 v178, v178, v180
	v_add_f32_e32 v179, v179, v181
	v_add_f32_e32 v180, v51, v43
	v_mul_f32_e32 v181, v51, v51
	v_fmac_f32_e32 v181, v43, v43
	v_add_f32_e32 v178, v178, v180
	v_add_f32_e32 v179, v179, v181
	v_add_f32_e32 v180, v36, v32
	v_mul_f32_e32 v181, v36, v36
	v_fmac_f32_e32 v181, v32, v32
	v_add_f32_e32 v178, v178, v180
	v_add_f32_e32 v179, v179, v181
	v_add_f32_e32 v180, v37, v33
	v_mul_f32_e32 v181, v37, v37
	v_fmac_f32_e32 v181, v33, v33
	v_add_f32_e32 v178, v178, v180
	v_add_f32_e32 v179, v179, v181
	v_add_f32_e32 v180, v38, v34
	v_mul_f32_e32 v181, v38, v38
	v_fmac_f32_e32 v181, v34, v34
	v_add_f32_e32 v178, v178, v180
	v_add_f32_e32 v179, v179, v181
	v_add_f32_e32 v180, v39, v35
	v_mul_f32_e32 v181, v39, v39
	v_fmac_f32_e32 v181, v35, v35
	v_add_f32_e32 v178, v178, v180
	v_add_f32_e32 v179, v179, v181
.Lg1e_nv5:
	v_cvt_pk_bf16_f32 v48, v48, v49
	v_cvt_pk_bf16_f32 v49, v50, v51
	v_cvt_pk_bf16_f32 v50, v40, v41
	v_cvt_pk_bf16_f32 v51, v42, v43
	global_store_dwordx4 v197, v[48:51], s[6:7]
	v_cvt_pk_bf16_f32 v36, v36, v37
	v_cvt_pk_bf16_f32 v37, v38, v39
	v_cvt_pk_bf16_f32 v38, v32, v33
	v_cvt_pk_bf16_f32 v39, v34, v35
	global_store_dwordx4 v197, v[36:39], s[6:7] offset:256
	v_mov_b32_e32 v40, v178
	v_mov_b32_e32 v41, v179
	v_add_u32_e32 v194, 0x48000, v197
	s_waitcnt vmcnt(8)
	v_pk_fma_f32 v[30:31], v[30:31], v[162:163], v[58:59] op_sel_hi:[1,0,1]
	v_pk_fma_f32 v[28:29], v[28:29], v[162:163], v[56:57] op_sel_hi:[1,0,1]
	v_pk_fma_f32 v[26:27], v[26:27], v[162:163], v[62:63] op_sel_hi:[1,0,1]
	v_pk_fma_f32 v[24:25], v[24:25], v[162:163], v[60:61] op_sel_hi:[1,0,1]
	v_pk_fma_f32 v[22:23], v[22:23], v[162:163], v[54:55] op_sel_hi:[1,0,1]
	v_pk_fma_f32 v[20:21], v[20:21], v[162:163], v[52:53] op_sel_hi:[1,0,1]
	v_pk_fma_f32 v[18:19], v[18:19], v[162:163], v[46:47] op_sel_hi:[1,0,1]
	v_pk_fma_f32 v[16:17], v[16:17], v[162:163], v[44:45] op_sel_hi:[1,0,1]
	s_cmp_lg_u32 s35, 8
	s_cbranch_scc1 .Lg1e_nv6
	v_add_f32_e32 v180, v28, v24
	v_mul_f32_e32 v181, v28, v28
	v_fmac_f32_e32 v181, v24, v24
	v_add_f32_e32 v178, 0, v180
	v_add_f32_e32 v179, 0, v181
	v_add_f32_e32 v180, v29, v25
	v_mul_f32_e32 v181, v29, v29
	v_fmac_f32_e32 v181, v25, v25
	v_add_f32_e32 v178, v178, v180
	v_add_f32_e32 v179, v179, v181
	v_add_f32_e32 v180, v30, v26
	v_mul_f32_e32 v181, v30, v30
	v_fmac_f32_e32 v181, v26, v26
	v_add_f32_e32 v178, v178, v180
	v_add_f32_e32 v179, v179, v181
	v_add_f32_e32 v180, v31, v27
	v_mul_f32_e32 v181, v31, v31
	v_fmac_f32_e32 v181, v27, v27
	v_add_f32_e32 v178, v178, v180
	v_add_f32_e32 v179, v179, v181
	v_add_f32_e32 v180, v20, v16
	v_mul_f32_e32 v181, v20, v20
	v_fmac_f32_e32 v181, v16, v16
	v_add_f32_e32 v178, v178, v180
	v_add_f32_e32 v179, v179, v181
	v_add_f32_e32 v180, v21, v17
	v_mul_f32_e32 v181, v21, v21
	v_fmac_f32_e32 v181, v17, v17
	v_add_f32_e32 v178, v178, v180
	v_add_f32_e32 v179, v179, v181
	v_add_f32_e32 v180, v22, v18
	v_mul_f32_e32 v181, v22, v22
	v_fmac_f32_e32 v181, v18, v18
	v_add_f32_e32 v178, v178, v180
	v_add_f32_e32 v179, v179, v181
	v_add_f32_e32 v180, v23, v19
	v_mul_f32_e32 v181, v23, v23
	v_fmac_f32_e32 v181, v19, v19
	v_add_f32_e32 v178, v178, v180
	v_add_f32_e32 v179, v179, v181
.Lg1e_nv6:
	v_cvt_pk_bf16_f32 v28, v28, v29
	v_cvt_pk_bf16_f32 v29, v30, v31
	v_cvt_pk_bf16_f32 v30, v24, v25
	v_cvt_pk_bf16_f32 v31, v26, v27
	global_store_dwordx4 v194, v[28:31], s[6:7]
	v_cvt_pk_bf16_f32 v20, v20, v21
	v_cvt_pk_bf16_f32 v21, v22, v23
	v_cvt_pk_bf16_f32 v22, v16, v17
	v_cvt_pk_bf16_f32 v23, v18, v19
	global_store_dwordx4 v194, v[20:23], s[6:7] offset:256
	v_mov_b32_e32 v24, v178
	v_mov_b32_e32 v25, v179
	v_add_u32_e32 v197, 0x48000, v194
	s_waitcnt vmcnt(4)
	v_pk_fma_f32 v[14:15], v[14:15], v[162:163], v[200:201] op_sel:[0,1,0] op_sel_hi:[1,1,1]
	v_pk_fma_f32 v[12:13], v[12:13], v[162:163], v[198:199] op_sel:[0,1,0] op_sel_hi:[1,1,1]
	v_pk_fma_f32 v[10:11], v[10:11], v[162:163], v[204:205] op_sel:[0,1,0] op_sel_hi:[1,1,1]
	v_pk_fma_f32 v[8:9], v[8:9], v[162:163], v[202:203] op_sel:[0,1,0] op_sel_hi:[1,1,1]
	v_pk_fma_f32 v[6:7], v[6:7], v[162:163], v[208:209] op_sel:[0,1,0] op_sel_hi:[1,1,1]
	v_pk_fma_f32 v[4:5], v[4:5], v[162:163], v[206:207] op_sel:[0,1,0] op_sel_hi:[1,1,1]
	v_pk_fma_f32 v[2:3], v[2:3], v[162:163], v[212:213] op_sel:[0,1,0] op_sel_hi:[1,1,1]
	v_pk_fma_f32 v[0:1], v[0:1], v[162:163], v[210:211] op_sel:[0,1,0] op_sel_hi:[1,1,1]
	s_cmp_lg_u32 s35, 8
	s_cbranch_scc1 .Lg1e_nv7
	v_add_f32_e32 v180, v12, v8
	v_mul_f32_e32 v181, v12, v12
	v_fmac_f32_e32 v181, v8, v8
	v_add_f32_e32 v178, 0, v180
	v_add_f32_e32 v179, 0, v181
	v_add_f32_e32 v180, v13, v9
	v_mul_f32_e32 v181, v13, v13
	v_fmac_f32_e32 v181, v9, v9
	v_add_f32_e32 v178, v178, v180
	v_add_f32_e32 v179, v179, v181
	v_add_f32_e32 v180, v14, v10
	v_mul_f32_e32 v181, v14, v14
	v_fmac_f32_e32 v181, v10, v10
	v_add_f32_e32 v178, v178, v180
	v_add_f32_e32 v179, v179, v181
	v_add_f32_e32 v180, v15, v11
	v_mul_f32_e32 v181, v15, v15
	v_fmac_f32_e32 v181, v11, v11
	v_add_f32_e32 v178, v178, v180
	v_add_f32_e32 v179, v179, v181
	v_add_f32_e32 v180, v4, v0
	v_mul_f32_e32 v181, v4, v4
	v_fmac_f32_e32 v181, v0, v0
	v_add_f32_e32 v178, v178, v180
	v_add_f32_e32 v179, v179, v181
	v_add_f32_e32 v180, v5, v1
	v_mul_f32_e32 v181, v5, v5
	v_fmac_f32_e32 v181, v1, v1
	v_add_f32_e32 v178, v178, v180
	v_add_f32_e32 v179, v179, v181
	v_add_f32_e32 v180, v6, v2
	v_mul_f32_e32 v181, v6, v6
	v_fmac_f32_e32 v181, v2, v2
	v_add_f32_e32 v178, v178, v180
	v_add_f32_e32 v179, v179, v181
	v_add_f32_e32 v180, v7, v3
	v_mul_f32_e32 v181, v7, v7
	v_fmac_f32_e32 v181, v3, v3
	v_add_f32_e32 v178, v178, v180
	v_add_f32_e32 v179, v179, v181
.Lg1e_nv7:
	v_cvt_pk_bf16_f32 v12, v12, v13
	v_cvt_pk_bf16_f32 v13, v14, v15
	v_cvt_pk_bf16_f32 v14, v8, v9
	v_cvt_pk_bf16_f32 v15, v10, v11
	global_store_dwordx4 v197, v[12:15], s[6:7]
	v_cvt_pk_bf16_f32 v4, v4, v5
	v_cvt_pk_bf16_f32 v5, v6, v7
	v_cvt_pk_bf16_f32 v6, v0, v1
	v_cvt_pk_bf16_f32 v7, v2, v3
	global_store_dwordx4 v197, v[4:7], s[6:7] offset:256
	v_mov_b32_e32 v8, v178
	v_mov_b32_e32 v9, v179
	s_cmp_lg_u32 s35, 8
	s_cbranch_scc1 .Lg1e_done
	ds_bpermute_b32 v138, v182, v136
	ds_bpermute_b32 v139, v182, v137
	ds_bpermute_b32 v122, v182, v120
	ds_bpermute_b32 v123, v182, v121
	ds_bpermute_b32 v106, v182, v104
	ds_bpermute_b32 v107, v182, v105
	ds_bpermute_b32 v90, v182, v88
	ds_bpermute_b32 v91, v182, v89
	ds_bpermute_b32 v74, v182, v72
	ds_bpermute_b32 v75, v182, v73
	ds_bpermute_b32 v42, v182, v40
	ds_bpermute_b32 v43, v182, v41
	ds_bpermute_b32 v26, v182, v24
	ds_bpermute_b32 v27, v182, v25
	ds_bpermute_b32 v10, v182, v8
	ds_bpermute_b32 v11, v182, v9
	s_waitcnt lgkmcnt(0)
	v_add_f32_e32 v136, v136, v138
	v_add_f32_e32 v137, v137, v139
	v_add_f32_e32 v120, v120, v122
	v_add_f32_e32 v121, v121, v123
	v_add_f32_e32 v104, v104, v106
	v_add_f32_e32 v105, v105, v107
	v_add_f32_e32 v88, v88, v90
	v_add_f32_e32 v89, v89, v91
	v_add_f32_e32 v72, v72, v74
	v_add_f32_e32 v73, v73, v75
	v_add_f32_e32 v40, v40, v42
	v_add_f32_e32 v41, v41, v43
	v_add_f32_e32 v24, v24, v26
	v_add_f32_e32 v25, v25, v27
	v_add_f32_e32 v8, v8, v10
	v_add_f32_e32 v9, v9, v11
	ds_bpermute_b32 v138, v183, v136
	ds_bpermute_b32 v139, v183, v137
	ds_bpermute_b32 v122, v183, v120
	ds_bpermute_b32 v123, v183, v121
	ds_bpermute_b32 v106, v183, v104
	ds_bpermute_b32 v107, v183, v105
	ds_bpermute_b32 v90, v183, v88
	ds_bpermute_b32 v91, v183, v89
	ds_bpermute_b32 v74, v183, v72
	ds_bpermute_b32 v75, v183, v73
	ds_bpermute_b32 v42, v183, v40
	ds_bpermute_b32 v43, v183, v41
	ds_bpermute_b32 v26, v183, v24
	ds_bpermute_b32 v27, v183, v25
	ds_bpermute_b32 v10, v183, v8
	ds_bpermute_b32 v11, v183, v9
	s_waitcnt lgkmcnt(0)
	v_add_f32_e32 v136, v136, v138
	v_add_f32_e32 v137, v137, v139
	v_add_f32_e32 v120, v120, v122
	v_add_f32_e32 v121, v121, v123
	v_add_f32_e32 v104, v104, v106
	v_add_f32_e32 v105, v105, v107
	v_add_f32_e32 v88, v88, v90
	v_add_f32_e32 v89, v89, v91
	v_add_f32_e32 v72, v72, v74
	v_add_f32_e32 v73, v73, v75
	v_add_f32_e32 v40, v40, v42
	v_add_f32_e32 v41, v41, v43
	v_add_f32_e32 v24, v24, v26
	v_add_f32_e32 v25, v25, v27
	v_add_f32_e32 v8, v8, v10
	v_add_f32_e32 v9, v9, v11
	s_and_saveexec_b64 s[38:39], s[72:73]
	v_lshl_add_u32 v240, v164, 7, s36
	global_store_dwordx2 v240, v[136:137], s[16:17]
	v_or_b32_e32 v181, 16, v164
	v_lshl_add_u32 v240, v181, 7, s36
	global_store_dwordx2 v240, v[120:121], s[16:17]
	v_or_b32_e32 v181, 32, v164
	v_lshl_add_u32 v240, v181, 7, s36
	global_store_dwordx2 v240, v[104:105], s[16:17]
	v_or_b32_e32 v181, 48, v164
	v_lshl_add_u32 v240, v181, 7, s36
	global_store_dwordx2 v240, v[88:89], s[16:17]
	v_add_u32_e32 v181, 0x80, v164
	v_lshl_add_u32 v240, v181, 7, s36
	global_store_dwordx2 v240, v[72:73], s[16:17]
	v_add_u32_e32 v181, 0x90, v164
	v_lshl_add_u32 v240, v181, 7, s36
	global_store_dwordx2 v240, v[40:41], s[16:17]
	v_add_u32_e32 v181, 0xa0, v164
	v_lshl_add_u32 v240, v181, 7, s36
	global_store_dwordx2 v240, v[24:25], s[16:17]
	v_add_u32_e32 v181, 0xb0, v164
	v_lshl_add_u32 v240, v181, 7, s36
	global_store_dwordx2 v240, v[8:9], s[16:17]
	s_or_b64 exec, exec, s[38:39]
.Lg1e_done:
.LBB0_561:
	s_andn2_b64 vcc, exec, s[22:23]
	s_mov_b64 s[22:23], -1
	s_cbranch_vccnz .LBB0_421
	s_andn2_b64 vcc, exec, s[14:15]
	s_cbranch_vccnz .LBB0_420
	s_barrier
	s_branch .LBB0_420
